# HGRN2/GDN: agent-scope fence (L2 write-back + L1 invalidate) dropped at the four same-workgroup sync points (pass ends, conv sweep hand-off), vmcnt(0)+barrier kept; HGRN2 stage 2b operand reads hoiste
# speedup vs baseline: 1.0270x; 1.0199x over previous
; __device__ __forceinline__ void phase_hg2(Frame& F, int j, bool ctx_out, bool dry = false) {
;     ...
;         for (int d = 0; d < 2; ++d) {
;             float lb0, lb1;
;     ...
;             __threadfence(); __syncthreads();
;         }
.LBB0_253:
	s_movk_i32 s72, 0x1800
	s_mov_b64 s[0:1], -1
	s_mov_b64 s[4:5], 0
	s_and_b64 vcc, exec, s[6:7]
	s_nop 0
	s_waitcnt vmcnt(0)
	s_nop 0
	s_barrier
	s_cbranch_vccnz .LBB0_249

; #define LAS __attribute__((address_space(3)))
; #define LDS_BARRIER() do { asm volatile("s_waitcnt lgkmcnt(0)" ::: "memory"); __builtin_amdgcn_s_barrier(); asm volatile("" ::: "memory"); } while (0)
; #define MFMA16(a, b, c) __builtin_amdgcn_mfma_f32_16x16x32_bf16((a), (b), (c), 0, 0, 0)
; __device__ __forceinline__ void phase_hg2(Frame& F, int j, bool ctx_out, bool dry = false) {
;     ...
;                     *(LAS v4u*)(KtT + (2 * c2) * HTS + seg * 8) = (v4u){k0[0] | (k0[1] << 16), k0[2] | (k0[3] << 16), k0[4] | (k0[5] << 16), k0[6] | (k0[7] << 16)};
;                     *(LAS v4u*)(KtT + (2 * c2 + 1) * HTS + seg * 8) = (v4u){k1[0] | (k1[1] << 16), k1[2] | (k1[3] << 16), k1[4] | (k1[5] << 16), k1[6] | (k1[7] << 16)};
;                 }
;                 LDS_BARRIER();
; #pragma unroll
;                 for (int kt = 0; kt < 8; ++kt) { const f32x4 e4 = *(const LAS f32x4*)(er + kt * 16 + q4 * 4); S[kt] = S[kt] * e4; }
; #pragma unroll
;                 for (int tl = 0; tl < 2; ++tl) { const int id = F.wave * 2 + tl, st = id >> 2, tt = id & 3;
;                     f32x4 a = (f32x4){0.f, 0.f, 0.f, 0.f};
;                     if (tt >= st) {
; #pragma unroll
;                         for (int ks = 0; ks < 4; ++ks) { const hb8 fa = *(const LAS hb8*)(Kt + (st * 16 + l15) * HQS + ks * 32 + q4 * 8), fb = *(const LAS hb8*)(Qt + (tt * 16 + l15) * HQS + ks * 32 + q4 * 8);
;                             a = MFMA16(fa, fb, a); }
;                     }
.LBB0_275:
	v_cndmask_b32_e64 v16, v29, v31, s[38:39]
	v_cndmask_b32_e64 v17, v28, v30, s[36:37]
	v_cvt_pk_bf16_f32 v19, v17, v16
	v_lshlrev_b32_e32 v16, 16, v190
	v_and_b32_e32 v17, 0xffff0000, v190
	v_pk_mul_f32 v[16:17], v[120:121], v[16:17]
	v_lshlrev_b32_e32 v18, 16, v19
	v_and_b32_e32 v19, 0xffff0000, v19
	v_cvt_pk_bf16_f32 v20, v114, v115
	v_cvt_pk_bf16_f32 v21, v116, v117
	v_pk_mul_f32 v[18:19], v[118:119], v[18:19]
	v_cvt_pk_bf16_f32 v16, v16, v17
	ds_write2_b32 v192, v20, v16 offset0:176 offset1:248
	v_cvt_pk_bf16_f32 v20, v18, v19
	v_and_b32_e32 v19, 0xffff, v21
	v_lshlrev_b32_e32 v16, 16, v193
	v_lshlrev_b32_e32 v17, 16, v197
	v_lshlrev_b32_e32 v18, 16, v201
	v_lshrrev_b32_e32 v22, 16, v195
	v_lshrrev_b32_e32 v23, 16, v196
	v_lshrrev_b32_e32 v24, 16, v200
	v_lshrrev_b32_e32 v25, 16, v21
	v_and_or_b32 v16, v195, s79, v16
	v_and_or_b32 v17, v196, s79, v17
	v_and_or_b32 v18, v200, s79, v18
	v_lshl_or_b32 v19, v20, 16, v19
	ds_write2_b32 v191, v21, v20 offset0:176 offset1:248
	ds_write_b128 v194, v[16:19] offset:36864
	v_and_or_b32 v16, v193, s77, v22
	v_and_or_b32 v17, v197, s77, v23
	v_and_or_b32 v18, v201, s77, v24
	v_and_or_b32 v19, v20, s77, v25
	ds_write_b128 v194, v[16:19] offset:37024
	v_lshlrev_b32_e32 v16, 4, v100
	v_add_u32_e32 v84, 0, v16
	s_waitcnt lgkmcnt(0)
	s_barrier
	v_add_u32_e32 v16, 0x1e800, v84
	ds_read_b128 v[40:43], v16
	ds_read_b128 v[44:47], v16 offset:64
	ds_read_b128 v[36:39], v16 offset:128
	ds_read_b128 v[32:35], v16 offset:192
	ds_read_b128 v[28:31], v16 offset:256
	ds_read_b128 v[24:27], v16 offset:320
	ds_read_b128 v[20:23], v16 offset:384
	ds_read_b128 v[16:19], v16 offset:448
	s_mov_b64 s[8:9], -1
	s_and_b64 vcc, exec, s[74:75]
	v_add_u32_e32 v85, s15, v177
	v_add_u32_e32 v86, s16, v177
	s_cbranch_vccz .LBB0_277
	v_mad_u64_u32 v[88:89], s[8:9], v85, s81, v[84:85]
	v_add_u32_e32 v90, s16, v177
	v_mad_u64_u32 v[108:109], s[8:9], v90, s81, v[84:85]
	ds_read_b128 v[208:211], v88 offset:18432
	ds_read_b128 v[212:215], v108
	ds_read_b128 v[216:219], v88 offset:18496
	ds_read_b128 v[220:223], v108 offset:64
	ds_read_b128 v[224:227], v88 offset:18560
	ds_read_b128 v[228:231], v108 offset:128
	ds_read_b128 v[232:235], v88 offset:18624
	ds_read_b128 v[236:239], v108 offset:192
	s_mov_b64 s[8:9], 0
	s_waitcnt lgkmcnt(6)
	v_mfma_f32_16x16x32_bf16 v[48:51], v[208:211], v[212:215], 0
	s_waitcnt lgkmcnt(4)
	v_mfma_f32_16x16x32_bf16 v[48:51], v[216:219], v[220:223], v[48:51]
	s_waitcnt lgkmcnt(2)
	v_mfma_f32_16x16x32_bf16 v[48:51], v[224:227], v[228:231], v[48:51]
	s_waitcnt lgkmcnt(0)
	v_mfma_f32_16x16x32_bf16 v[48:51], v[232:235], v[236:239], v[48:51]

; #define LAS __attribute__((address_space(3)))
; __device__ __forceinline__ unsigned pk2(float lo, float hi) { const f32x2_t v = {lo, hi}; return __builtin_bit_cast(unsigned, __builtin_convertvector(v, bf16x2_t)); }
; #define MFMA16(a, b, c) __builtin_amdgcn_mfma_f32_16x16x32_bf16((a), (b), (c), 0, 0, 0)
; __device__ __forceinline__ void phase_hg2(Frame& F, int j, bool ctx_out, bool dry = false) {
;     ...
;                 for (int tl = 0; tl < 2; ++tl) { const int id = F.wave * 2 + tl, st = id >> 2, tt = id & 3;
;                     f32x4 a = (f32x4){0.f, 0.f, 0.f, 0.f};
;                     if (tt >= st) {
; #pragma unroll
;                         for (int ks = 0; ks < 4; ++ks) { const hb8 fa = *(const LAS hb8*)(Kt + (st * 16 + l15) * HQS + ks * 32 + q4 * 8), fb = *(const LAS hb8*)(Qt + (tt * 16 + l15) * HQS + ks * 32 + q4 * 8);
;                             a = MFMA16(fa, fb, a); }
;                     }
;                     const int tg = tt * 16 + l15, sg = st * 16 + q4 * 4;
;                     const float a0 = (sg + 0 <= tg) ? a.x : 0.f, a1 = (sg + 1 <= tg) ? a.y : 0.f, a2 = (sg + 2 <= tg) ? a.z : 0.f, a3 = (sg + 3 <= tg) ? a.w : 0.f;
;                     *(LAS v2u*)(ATT + tg * HTS + sg) = (v2u){pk2(a0, a1), pk2(a2, a3)}; }
.LBB0_279:
	v_lshlrev_b32_e32 v86, 2, v100
	v_add_u32_e32 v87, s15, v86
	v_cmp_le_i32_e32 vcc, v87, v90
	v_or_b32_e32 v88, 2, v87
	v_or_b32_e32 v89, 3, v87
	s_nop 0
	v_cndmask_b32_e32 v48, 0, v48, vcc
	v_cmp_lt_i32_e32 vcc, v87, v90
	s_mov_b64 s[8:9], -1
	v_add_u32_e32 v92, s17, v177
	v_cndmask_b32_e32 v49, 0, v49, vcc
	v_cmp_le_i32_e32 vcc, v88, v90
	v_cvt_pk_bf16_f32 v48, v48, v49
	s_nop 0
	v_cndmask_b32_e32 v50, 0, v50, vcc
	v_cmp_le_i32_e32 vcc, v89, v90
	s_nop 1
	v_cndmask_b32_e32 v51, 0, v51, vcc
	v_cvt_pk_bf16_f32 v49, v50, v51
	v_mul_lo_u32 v50, v90, s82
	v_lshlrev_b32_e32 v90, 1, v87
	v_add3_u32 v50, s83, v50, v90
	s_and_b64 vcc, exec, s[92:93]
	ds_write_b64 v50, v[48:49]
	s_cbranch_vccz .LBB0_281
	v_mad_u64_u32 v[98:99], s[8:9], v85, s81, v[84:85]
	v_add_u32_e32 v91, s17, v177
	v_mad_u64_u32 v[112:113], s[8:9], v91, s81, v[84:85]
	ds_read_b128 v[208:211], v98 offset:18432
	ds_read_b128 v[212:215], v112
	ds_read_b128 v[216:219], v98 offset:18496
	ds_read_b128 v[220:223], v112 offset:64
	ds_read_b128 v[224:227], v98 offset:18560
	ds_read_b128 v[228:231], v112 offset:128
	ds_read_b128 v[232:235], v98 offset:18624
	ds_read_b128 v[236:239], v112 offset:192
	s_mov_b64 s[8:9], 0
	s_waitcnt lgkmcnt(6)
	v_mfma_f32_16x16x32_bf16 v[48:51], v[208:211], v[212:215], 0
	s_waitcnt lgkmcnt(4)
	v_mfma_f32_16x16x32_bf16 v[48:51], v[216:219], v[220:223], v[48:51]
	s_waitcnt lgkmcnt(2)
	v_mfma_f32_16x16x32_bf16 v[48:51], v[224:227], v[228:231], v[48:51]
	s_waitcnt lgkmcnt(0)
	v_mfma_f32_16x16x32_bf16 v[48:51], v[232:235], v[236:239], v[48:51]

; __device__ __forceinline__ void gdn_conv_sweep(Frame& F, int b, int hq) {
;     ...
;     __threadfence(); __syncthreads();
; }
; __device__ __forceinline__ void phase_gdn2(Frame& F, bool ctx_out, bool dry = false) {
;     ...
;       gdn_conv_sweep(F, item2 >> 4, item2 & 15);
;       for (int ev = 0; ev < 2; ++ev) {
;         const int item = item2 * 2 + ev;
;         const int b = item >> 5, hv = item & 31, hq = hv >> 1;
.LBB0_943:
	v_readlane_b32 s0, v255, 10
	s_lshl_b32 s0, s0, 1
	s_and_b32 s0, s0, 30
	s_lshl_b32 s4, s0, 6
	v_writelane_b32 v255, s0, 17
	s_lshl_b32 s0, s0, 13
	s_add_u32 s5, s51, s0
	s_addc_u32 s6, s52, 0
	s_add_i32 s7, s41, 0x103f
	s_addk_i32 s41, 0x1007
	s_mov_b32 s3, 0
	s_mov_b64 s[0:1], -1
	s_nop 0
	s_waitcnt vmcnt(0)
	s_nop 0
	s_barrier
	s_branch .LBB0_945

; __device__ __forceinline__ void phase_gdn2(Frame& F, bool ctx_out, bool dry = false) {
;     ...
;         for (int d = 0; d < 2; ++d) {
;     ...
;             __threadfence(); __syncthreads();
;         }
.LBB0_955:
	s_mov_b32 s3, 1
	s_mov_b64 s[26:27], -1
	s_mov_b64 s[28:29], 0
	s_and_b64 vcc, exec, s[24:25]
	s_nop 0
	s_waitcnt vmcnt(0) lgkmcnt(0)
	s_nop 0
	s_barrier
	s_cbranch_vccnz .LBB0_944

; __device__ __forceinline__ void phase_hg2(Frame& F, int j, bool ctx_out, bool dry = false) {
;     ...
;         for (int d = 0; d < 2; ++d) {
;             float lb0, lb1;
;     ...
;             __threadfence(); __syncthreads();
;         }
.LBB0_2343:
	s_movk_i32 s7, 0x800
	s_mov_b64 s[92:93], -1
	s_mov_b64 s[74:75], 0
	s_and_b64 vcc, exec, s[0:1]
	s_nop 0
	s_waitcnt vmcnt(0)
	s_nop 0
	s_barrier
	s_cbranch_vccnz .LBB0_2339

; #define LAS __attribute__((address_space(3)))
; #define LDS_BARRIER() do { asm volatile("s_waitcnt lgkmcnt(0)" ::: "memory"); __builtin_amdgcn_s_barrier(); asm volatile("" ::: "memory"); } while (0)
; #define MFMA16(a, b, c) __builtin_amdgcn_mfma_f32_16x16x32_bf16((a), (b), (c), 0, 0, 0)
; __device__ __forceinline__ void phase_hg2(Frame& F, int j, bool ctx_out, bool dry = false) {
;     ...
;                     *(LAS v4u*)(KtT + (2 * c2) * HTS + seg * 8) = (v4u){k0[0] | (k0[1] << 16), k0[2] | (k0[3] << 16), k0[4] | (k0[5] << 16), k0[6] | (k0[7] << 16)};
;                     *(LAS v4u*)(KtT + (2 * c2 + 1) * HTS + seg * 8) = (v4u){k1[0] | (k1[1] << 16), k1[2] | (k1[3] << 16), k1[4] | (k1[5] << 16), k1[6] | (k1[7] << 16)};
;                 }
;                 LDS_BARRIER();
; #pragma unroll
;                 for (int kt = 0; kt < 8; ++kt) { const f32x4 e4 = *(const LAS f32x4*)(er + kt * 16 + q4 * 4); S[kt] = S[kt] * e4; }
; #pragma unroll
;                 for (int tl = 0; tl < 2; ++tl) { const int id = F.wave * 2 + tl, st = id >> 2, tt = id & 3;
;                     f32x4 a = (f32x4){0.f, 0.f, 0.f, 0.f};
;                     if (tt >= st) {
; #pragma unroll
;                         for (int ks = 0; ks < 4; ++ks) { const hb8 fa = *(const LAS hb8*)(Kt + (st * 16 + l15) * HQS + ks * 32 + q4 * 8), fb = *(const LAS hb8*)(Qt + (tt * 16 + l15) * HQS + ks * 32 + q4 * 8);
;                             a = MFMA16(fa, fb, a); }
;                     }
.LBB0_2365:
	v_cndmask_b32_e64 v17, v29, v31, s[40:41]
	v_cndmask_b32_e64 v16, v28, v30, s[38:39]
	v_pk_mul_f32 v[16:17], v[112:113], v[16:17]
	v_cvt_pk_bf16_f32 v20, v120, v121
	v_cvt_pk_bf16_f32 v19, v16, v17
	v_lshlrev_b32_e32 v16, 16, v196
	v_and_b32_e32 v17, 0xffff0000, v196
	v_pk_mul_f32 v[16:17], v[126:127], v[16:17]
	v_lshlrev_b32_e32 v18, 16, v19
	v_and_b32_e32 v19, 0xffff0000, v19
	v_cvt_pk_bf16_f32 v21, v122, v123
	v_pk_mul_f32 v[18:19], v[124:125], v[18:19]
	v_cvt_pk_bf16_f32 v16, v16, v17
	ds_write2_b32 v198, v20, v16 offset0:176 offset1:248
	v_cvt_pk_bf16_f32 v20, v18, v19
	v_and_b32_e32 v19, 0xffff, v21
	v_lshlrev_b32_e32 v16, 16, v199
	v_lshlrev_b32_e32 v17, 16, v203
	v_lshlrev_b32_e32 v18, 16, v207
	v_lshrrev_b32_e32 v22, 16, v201
	v_lshrrev_b32_e32 v23, 16, v202
	v_lshrrev_b32_e32 v24, 16, v206
	v_lshrrev_b32_e32 v25, 16, v21
	v_and_or_b32 v16, v201, s11, v16
	v_and_or_b32 v17, v202, s11, v17
	v_and_or_b32 v18, v206, s11, v18
	v_lshl_or_b32 v19, v20, 16, v19
	ds_write2_b32 v197, v21, v20 offset0:176 offset1:248
	ds_write_b128 v200, v[16:19] offset:36864
	v_and_or_b32 v16, v199, s9, v22
	v_and_or_b32 v17, v203, s9, v23
	v_and_or_b32 v18, v207, s9, v24
	v_and_or_b32 v19, v20, s9, v25
	ds_write_b128 v200, v[16:19] offset:37024
	v_lshlrev_b32_e32 v16, 4, v102
	v_add_u32_e32 v84, 0, v16
	s_waitcnt lgkmcnt(0)
	s_barrier
	v_add_u32_e32 v16, 0x1e800, v84
	ds_read_b128 v[40:43], v16
	ds_read_b128 v[44:47], v16 offset:64
	ds_read_b128 v[36:39], v16 offset:128
	ds_read_b128 v[32:35], v16 offset:192
	ds_read_b128 v[28:31], v16 offset:256
	ds_read_b128 v[24:27], v16 offset:320
	ds_read_b128 v[20:23], v16 offset:384
	ds_read_b128 v[16:19], v16 offset:448
	s_mov_b64 s[38:39], -1
	s_and_b64 vcc, exec, s[80:81]
	v_add_u32_e32 v85, s73, v183
	v_add_u32_e32 v86, s4, v183
	s_cbranch_vccz .LBB0_2367
	v_mad_u64_u32 v[88:89], s[38:39], v85, s13, v[84:85]
	v_add_u32_e32 v90, s4, v183
	v_mad_u64_u32 v[114:115], s[38:39], v90, s13, v[84:85]
	ds_read_b128 v[208:211], v88 offset:18432
	ds_read_b128 v[212:215], v114
	ds_read_b128 v[216:219], v88 offset:18496
	ds_read_b128 v[220:223], v114 offset:64
	ds_read_b128 v[224:227], v88 offset:18560
	ds_read_b128 v[228:231], v114 offset:128
	ds_read_b128 v[232:235], v88 offset:18624
	ds_read_b128 v[236:239], v114 offset:192
	s_mov_b64 s[38:39], 0
	s_waitcnt lgkmcnt(6)
	v_mfma_f32_16x16x32_bf16 v[48:51], v[208:211], v[212:215], 0
	s_waitcnt lgkmcnt(4)
	v_mfma_f32_16x16x32_bf16 v[48:51], v[216:219], v[220:223], v[48:51]
	s_waitcnt lgkmcnt(2)
	v_mfma_f32_16x16x32_bf16 v[48:51], v[224:227], v[228:231], v[48:51]
	s_waitcnt lgkmcnt(0)
	v_mfma_f32_16x16x32_bf16 v[48:51], v[232:235], v[236:239], v[48:51]

; #define LAS __attribute__((address_space(3)))
; __device__ __forceinline__ unsigned pk2(float lo, float hi) { const f32x2_t v = {lo, hi}; return __builtin_bit_cast(unsigned, __builtin_convertvector(v, bf16x2_t)); }
; #define MFMA16(a, b, c) __builtin_amdgcn_mfma_f32_16x16x32_bf16((a), (b), (c), 0, 0, 0)
; __device__ __forceinline__ void phase_hg2(Frame& F, int j, bool ctx_out, bool dry = false) {
;     ...
;                 for (int tl = 0; tl < 2; ++tl) { const int id = F.wave * 2 + tl, st = id >> 2, tt = id & 3;
;                     f32x4 a = (f32x4){0.f, 0.f, 0.f, 0.f};
;                     if (tt >= st) {
; #pragma unroll
;                         for (int ks = 0; ks < 4; ++ks) { const hb8 fa = *(const LAS hb8*)(Kt + (st * 16 + l15) * HQS + ks * 32 + q4 * 8), fb = *(const LAS hb8*)(Qt + (tt * 16 + l15) * HQS + ks * 32 + q4 * 8);
;                             a = MFMA16(fa, fb, a); }
;                     }
;                     const int tg = tt * 16 + l15, sg = st * 16 + q4 * 4;
;                     const float a0 = (sg + 0 <= tg) ? a.x : 0.f, a1 = (sg + 1 <= tg) ? a.y : 0.f, a2 = (sg + 2 <= tg) ? a.z : 0.f, a3 = (sg + 3 <= tg) ? a.w : 0.f;
;                     *(LAS v2u*)(ATT + tg * HTS + sg) = (v2u){pk2(a0, a1), pk2(a2, a3)}; }
.LBB0_2369:
	v_lshlrev_b32_e32 v86, 2, v102
	v_add_u32_e32 v87, s73, v86
	v_cmp_le_i32_e32 vcc, v87, v90
	v_or_b32_e32 v88, 2, v87
	v_or_b32_e32 v89, 3, v87
	s_nop 0
	v_cndmask_b32_e32 v48, 0, v48, vcc
	v_cmp_lt_i32_e32 vcc, v87, v90
	s_mov_b64 s[38:39], -1
	v_add_u32_e32 v92, s5, v183
	v_cndmask_b32_e32 v49, 0, v49, vcc
	v_cmp_le_i32_e32 vcc, v88, v90
	v_cvt_pk_bf16_f32 v48, v48, v49
	s_nop 0
	v_cndmask_b32_e32 v50, 0, v50, vcc
	v_cmp_le_i32_e32 vcc, v89, v90
	s_nop 1
	v_cndmask_b32_e32 v51, 0, v51, vcc
	v_cvt_pk_bf16_f32 v49, v50, v51
	v_mul_lo_u32 v50, v90, s14
	v_lshlrev_b32_e32 v90, 1, v87
	v_add3_u32 v50, s15, v50, v90
	s_and_b64 vcc, exec, s[84:85]
	ds_write_b64 v50, v[48:49]
	s_cbranch_vccz .LBB0_2371
	v_mad_u64_u32 v[98:99], s[38:39], v85, s13, v[84:85]
	v_add_u32_e32 v91, s5, v183
	v_mad_u64_u32 v[118:119], s[38:39], v91, s13, v[84:85]
	ds_read_b128 v[208:211], v98 offset:18432
	ds_read_b128 v[212:215], v118
	ds_read_b128 v[216:219], v98 offset:18496
	ds_read_b128 v[220:223], v118 offset:64
	ds_read_b128 v[224:227], v98 offset:18560
	ds_read_b128 v[228:231], v118 offset:128
	ds_read_b128 v[232:235], v98 offset:18624
	ds_read_b128 v[236:239], v118 offset:192
	s_mov_b64 s[38:39], 0
	s_waitcnt lgkmcnt(6)
	v_mfma_f32_16x16x32_bf16 v[48:51], v[208:211], v[212:215], 0
	s_waitcnt lgkmcnt(4)
	v_mfma_f32_16x16x32_bf16 v[48:51], v[216:219], v[220:223], v[48:51]
	s_waitcnt lgkmcnt(2)
	v_mfma_f32_16x16x32_bf16 v[48:51], v[224:227], v[228:231], v[48:51]
	s_waitcnt lgkmcnt(0)
	v_mfma_f32_16x16x32_bf16 v[48:51], v[232:235], v[236:239], v[48:51]
